# combo + phase-B items-first flag taken from the hardware wave-slot id (HW_ID bit0) of wave 0, LDS-broadcast
# baseline (speedup 1.0000x reference)
; __global__ void __launch_bounds__(256, 2) hybrid_megakernel(Params p) {
;     ...
;     for (int vb = bid; vb < 512; vb += nb) {
;       { const int q2 = vb >> 3; inproj_tile<4>(p, l, (vb & 7) * 16 + (q2 & 15), 8 + (q2 >> 4), lds); }
;       if (vb < 64) cmp_item(p, l, vb, lds);
;       else {
;         const int j = vb - 64;
;         if (vb >= 256) { const int i2 = (vb - 256) >> 3; inproj_tile<2>(p, l, (vb & 7) * 16 + (i2 & 15), 24 + (i2 >> 4), lds); }
;         win_item(p, j, lds);
;         if (j + 448 < 512) win_item(p, j + 448, lds);
;         for (int it = j; it < 1536; it += 448) dil_item(p, it, lds);
;       }
;     }
.LBB0_213:
	s_or_b64 exec, exec, s[0:1]
	v_readlane_b32 s0, v235, 23
	v_readlane_b32 s1, v235, 24
	s_andn2_b64 vcc, exec, s[0:1]
	s_waitcnt lgkmcnt(0)
	v_cndmask_b32_e64 v0, 0, 1, s[0:1]
	v_cmp_ne_u32_e64 s[2:3], 1, v0
	s_barrier
	s_nop 0
	v_writelane_b32 v234, s2, 27
	s_nop 1
	v_writelane_b32 v234, s3, 28
	s_cbranch_vccnz .LBB0_298
	v_readlane_b32 s0, v234, 24
	s_mul_i32 s28, s0, 0xd00
	s_lshl_b32 s29, s0, 1
	v_readlane_b32 s30, v234, 18
	v_readlane_b32 s31, v234, 17
	v_readlane_b32 s34, v234, 14
	v_readlane_b32 s35, v234, 13
	v_readlane_b32 s36, v235, 0
	s_getreg_b32 s98, hwreg(HW_REG_HW_ID, 0, 4)
	s_and_b32 s98, s98, 1
	v_mov_b32_e32 v0, 0x11ff8
	v_mov_b32_e32 v1, s98
	v_cmp_gt_u32_e32 vcc, 64, v176
	s_and_saveexec_b64 s[0:1], vcc
	ds_write_b32 v0, v1
	s_or_b64 exec, exec, s[0:1]
	s_waitcnt lgkmcnt(0)
	s_barrier
	ds_read_b32 v1, v0
	s_waitcnt lgkmcnt(0)
	s_nop 0
	v_readfirstlane_b32 s98, v1
	s_barrier
	s_branch .LBB0_217
